# GEMM K-loops (in-proj, out-proj): LDS-DMA loads in scalar-base form, no per-load 64-bit VALU address adds
# speedup vs baseline: 1.0057x; 1.0009x over previous
.LBB0_140:
	s_add_u32 s10, s8, 0xfff80080
	s_addc_u32 s11, s9, -1
	s_add_i32 s60, 0, 0x10000
	s_cmp_eq_u32 s59, 28
	s_cselect_b32 s15, s0, s11
	s_cselect_b32 s14, s1, s10
	v_add_u32_e32 v0, s60, v167
	s_cselect_b32 s11, s25, s58
	s_cselect_b32 s10, s27, s57
	s_add_i32 s62, 0, 0x14000
	ds_read_b128 v[130:133], v0
	ds_read_b128 v[158:161], v0 offset:1024
	ds_read_b128 v[162:165], v0 offset:2048
	ds_read_b128 v[170:173], v0 offset:3072
	v_add_u32_e32 v0, s62, v167
	ds_read_b128 v[174:177], v0
	ds_read_b128 v[178:181], v0 offset:1024
	ds_read_b128 v[182:185], v0 offset:2048
	ds_read_b128 v[186:189], v0 offset:3072
	s_add_i32 m0, s48, 0xc000
	ds_read_b128 v[190:193], v169
	ds_read_b128 v[194:197], v169 offset:1024
	ds_read_b128 v[198:201], v169 offset:2048
	ds_read_b128 v[216:219], v169 offset:3072
	ds_read_b128 v[220:223], v169 offset:4096
	ds_read_b128 v[224:227], v169 offset:5120
	ds_read_b128 v[228:231], v169 offset:6144
	ds_read_b128 v[232:235], v169 offset:7168
	global_load_lds_dwordx4 v156, s[8:9]
	s_add_i32 m0, s48, 0xe000
	s_nop 0
	global_load_lds_dwordx4 v146, s[8:9]
	s_waitcnt vmcnt(8)
	s_waitcnt lgkmcnt(0)
	s_barrier
	s_setprio 1
	s_waitcnt lgkmcnt(0)
	v_mfma_f32_16x16x32_bf16 v[126:129], v[130:133], v[190:193], v[126:129]
	v_mfma_f32_16x16x32_bf16 v[122:125], v[162:165], v[190:193], v[122:125]
	v_mfma_f32_16x16x32_bf16 v[110:113], v[130:133], v[198:201], v[110:113]
	v_mfma_f32_16x16x32_bf16 v[106:109], v[162:165], v[198:201], v[106:109]
	v_mfma_f32_16x16x32_bf16 v[94:97], v[130:133], v[220:223], v[94:97]
	v_mfma_f32_16x16x32_bf16 v[90:93], v[162:165], v[220:223], v[90:93]
	v_mfma_f32_16x16x32_bf16 v[78:81], v[130:133], v[228:231], v[78:81]
	v_mfma_f32_16x16x32_bf16 v[74:77], v[162:165], v[228:231], v[74:77]
	v_mfma_f32_16x16x32_bf16 v[126:129], v[158:161], v[194:197], v[126:129]
	v_mfma_f32_16x16x32_bf16 v[122:125], v[170:173], v[194:197], v[122:125]
	v_mfma_f32_16x16x32_bf16 v[110:113], v[158:161], v[216:219], v[110:113]
	v_mfma_f32_16x16x32_bf16 v[106:109], v[170:173], v[216:219], v[106:109]
	v_mfma_f32_16x16x32_bf16 v[94:97], v[158:161], v[224:227], v[94:97]
	v_mfma_f32_16x16x32_bf16 v[90:93], v[170:173], v[224:227], v[90:93]
	v_mfma_f32_16x16x32_bf16 v[78:81], v[158:161], v[232:235], v[78:81]
	v_mfma_f32_16x16x32_bf16 v[74:77], v[170:173], v[232:235], v[74:77]
	s_setprio 0
	s_setprio 1
	v_mfma_f32_16x16x32_bf16 v[118:121], v[174:177], v[190:193], v[118:121]
	v_mfma_f32_16x16x32_bf16 v[114:117], v[182:185], v[190:193], v[114:117]
	v_mfma_f32_16x16x32_bf16 v[102:105], v[174:177], v[198:201], v[102:105]
	v_mfma_f32_16x16x32_bf16 v[98:101], v[182:185], v[198:201], v[98:101]
	v_mfma_f32_16x16x32_bf16 v[86:89], v[174:177], v[220:223], v[86:89]
	v_mfma_f32_16x16x32_bf16 v[82:85], v[182:185], v[220:223], v[82:85]
	v_mfma_f32_16x16x32_bf16 v[70:73], v[174:177], v[228:231], v[70:73]
	v_mfma_f32_16x16x32_bf16 v[66:69], v[182:185], v[228:231], v[66:69]
	v_mfma_f32_16x16x32_bf16 v[118:121], v[178:181], v[194:197], v[118:121]
	v_mfma_f32_16x16x32_bf16 v[114:117], v[186:189], v[194:197], v[114:117]
	v_mfma_f32_16x16x32_bf16 v[102:105], v[178:181], v[216:219], v[102:105]
	v_mfma_f32_16x16x32_bf16 v[98:101], v[186:189], v[216:219], v[98:101]
	v_mfma_f32_16x16x32_bf16 v[86:89], v[178:181], v[224:227], v[86:89]
	v_mfma_f32_16x16x32_bf16 v[82:85], v[186:189], v[224:227], v[82:85]
	v_mfma_f32_16x16x32_bf16 v[70:73], v[178:181], v[232:235], v[70:73]
	v_mfma_f32_16x16x32_bf16 v[66:69], v[186:189], v[232:235], v[66:69]
	s_setprio 0
	s_barrier
	s_add_i32 s60, s60, s29
	s_add_u32 s72, s10, s44
	s_addc_u32 s73, s11, s45
	s_mov_b32 m0, s60
	ds_read_b128 v[190:193], v169 offset:16384
	ds_read_b128 v[194:197], v169 offset:17408
	ds_read_b128 v[198:201], v169 offset:18432
	ds_read_b128 v[216:219], v169 offset:19456
	ds_read_b128 v[220:223], v169 offset:20480
	ds_read_b128 v[224:227], v169 offset:21504
	ds_read_b128 v[228:231], v169 offset:22528
	ds_read_b128 v[232:235], v169 offset:23552
	global_load_lds_dwordx4 v138, s[10:11]
	s_add_i32 m0, s60, 0x2000
	s_add_u32 s60, s10, 0x80000
	s_addc_u32 s61, s11, 0
	s_add_i32 s62, s62, s29
	global_load_lds_dwordx4 v134, s[10:11]
	s_mov_b32 m0, s62
	s_add_u32 s74, s14, s44
	s_addc_u32 s75, s15, s45
	global_load_lds_dwordx4 v138, s[60:61]
	s_add_i32 m0, s62, 0x2000
	s_nop 0
	global_load_lds_dwordx4 v134, s[60:61]
	s_mov_b32 m0, s48
	s_nop 0
	global_load_lds_dwordx4 v140, s[14:15]
	s_mov_b32 m0, s49
	s_nop 0
	global_load_lds_dwordx4 v136, s[14:15]
	s_waitcnt vmcnt(8)
	s_waitcnt lgkmcnt(0)
	s_barrier
	s_setprio 1
	s_waitcnt lgkmcnt(0)
	v_mfma_f32_16x16x32_bf16 v[62:65], v[130:133], v[190:193], v[62:65]
	v_mfma_f32_16x16x32_bf16 v[58:61], v[162:165], v[190:193], v[58:61]
	v_mfma_f32_16x16x32_bf16 v[46:49], v[130:133], v[198:201], v[46:49]
	v_mfma_f32_16x16x32_bf16 v[42:45], v[162:165], v[198:201], v[42:45]
	v_mfma_f32_16x16x32_bf16 v[30:33], v[130:133], v[220:223], v[30:33]
	v_mfma_f32_16x16x32_bf16 v[26:29], v[162:165], v[220:223], v[26:29]
	v_mfma_f32_16x16x32_bf16 v[14:17], v[130:133], v[228:231], v[14:17]
	v_mfma_f32_16x16x32_bf16 v[10:13], v[162:165], v[228:231], v[10:13]
	v_mfma_f32_16x16x32_bf16 v[62:65], v[158:161], v[194:197], v[62:65]
	v_mfma_f32_16x16x32_bf16 v[58:61], v[170:173], v[194:197], v[58:61]
	v_mfma_f32_16x16x32_bf16 v[46:49], v[158:161], v[216:219], v[46:49]
	v_mfma_f32_16x16x32_bf16 v[42:45], v[170:173], v[216:219], v[42:45]
	v_mfma_f32_16x16x32_bf16 v[30:33], v[158:161], v[224:227], v[30:33]
	v_mfma_f32_16x16x32_bf16 v[26:29], v[170:173], v[224:227], v[26:29]
	v_mfma_f32_16x16x32_bf16 v[14:17], v[158:161], v[232:235], v[14:17]
	v_mfma_f32_16x16x32_bf16 v[10:13], v[170:173], v[232:235], v[10:13]
	s_setprio 0
	s_setprio 1
	v_mfma_f32_16x16x32_bf16 v[54:57], v[174:177], v[190:193], v[54:57]
	v_mfma_f32_16x16x32_bf16 v[50:53], v[182:185], v[190:193], v[50:53]
	v_mfma_f32_16x16x32_bf16 v[38:41], v[174:177], v[198:201], v[38:41]
	v_mfma_f32_16x16x32_bf16 v[34:37], v[182:185], v[198:201], v[34:37]
	v_mfma_f32_16x16x32_bf16 v[22:25], v[174:177], v[220:223], v[22:25]
	v_mfma_f32_16x16x32_bf16 v[18:21], v[182:185], v[220:223], v[18:21]
	v_mfma_f32_16x16x32_bf16 v[6:9], v[174:177], v[228:231], v[6:9]
	v_mfma_f32_16x16x32_bf16 v[2:5], v[182:185], v[228:231], v[2:5]
	v_mfma_f32_16x16x32_bf16 v[54:57], v[178:181], v[194:197], v[54:57]
	v_mfma_f32_16x16x32_bf16 v[50:53], v[186:189], v[194:197], v[50:53]
	v_mfma_f32_16x16x32_bf16 v[38:41], v[178:181], v[216:219], v[38:41]
	v_mfma_f32_16x16x32_bf16 v[34:37], v[186:189], v[216:219], v[34:37]
	v_mfma_f32_16x16x32_bf16 v[22:25], v[178:181], v[224:227], v[22:25]
	v_mfma_f32_16x16x32_bf16 v[18:21], v[186:189], v[224:227], v[18:21]
	v_mfma_f32_16x16x32_bf16 v[6:9], v[178:181], v[232:235], v[6:9]
	v_mfma_f32_16x16x32_bf16 v[2:5], v[186:189], v[232:235], v[2:5]
	s_setprio 0
	s_barrier
	s_add_i32 s60, 0, 0x18000
	v_add_u32_e32 v0, s60, v167
	s_add_i32 s61, 0, 0x1c000
	ds_read_b128 v[130:133], v0
	ds_read_b128 v[158:161], v0 offset:1024
	ds_read_b128 v[162:165], v0 offset:2048
	ds_read_b128 v[170:173], v0 offset:3072
	v_add_u32_e32 v0, s61, v167
	ds_read_b128 v[174:177], v0
	ds_read_b128 v[178:181], v0 offset:1024
	ds_read_b128 v[182:185], v0 offset:2048
	ds_read_b128 v[186:189], v0 offset:3072
	s_add_u32 s14, s14, 0x80000
	s_addc_u32 s15, s15, 0
	s_mov_b32 m0, s50
	ds_read_b128 v[190:193], v169 offset:32768
	ds_read_b128 v[194:197], v169 offset:33792
	ds_read_b128 v[198:201], v169 offset:34816
	ds_read_b128 v[216:219], v169 offset:35840
	ds_read_b128 v[220:223], v169 offset:36864
	ds_read_b128 v[224:227], v169 offset:37888
	ds_read_b128 v[228:231], v169 offset:38912
	ds_read_b128 v[232:235], v169 offset:39936
	global_load_lds_dwordx4 v140, s[14:15]
	s_mov_b32 m0, s51
	s_nop 0
	global_load_lds_dwordx4 v136, s[14:15]
	s_waitcnt vmcnt(8)
	s_waitcnt lgkmcnt(0)
	s_barrier
	s_setprio 1
	s_waitcnt lgkmcnt(0)
	v_mfma_f32_16x16x32_bf16 v[126:129], v[130:133], v[190:193], v[126:129]
	v_mfma_f32_16x16x32_bf16 v[122:125], v[162:165], v[190:193], v[122:125]
	v_mfma_f32_16x16x32_bf16 v[110:113], v[130:133], v[198:201], v[110:113]
	v_mfma_f32_16x16x32_bf16 v[106:109], v[162:165], v[198:201], v[106:109]
	v_mfma_f32_16x16x32_bf16 v[94:97], v[130:133], v[220:223], v[94:97]
	v_mfma_f32_16x16x32_bf16 v[90:93], v[162:165], v[220:223], v[90:93]
	v_mfma_f32_16x16x32_bf16 v[78:81], v[130:133], v[228:231], v[78:81]
	v_mfma_f32_16x16x32_bf16 v[74:77], v[162:165], v[228:231], v[74:77]
	v_mfma_f32_16x16x32_bf16 v[126:129], v[158:161], v[194:197], v[126:129]
	v_mfma_f32_16x16x32_bf16 v[122:125], v[170:173], v[194:197], v[122:125]
	v_mfma_f32_16x16x32_bf16 v[110:113], v[158:161], v[216:219], v[110:113]
	v_mfma_f32_16x16x32_bf16 v[106:109], v[170:173], v[216:219], v[106:109]
	v_mfma_f32_16x16x32_bf16 v[94:97], v[158:161], v[224:227], v[94:97]
	v_mfma_f32_16x16x32_bf16 v[90:93], v[170:173], v[224:227], v[90:93]
	v_mfma_f32_16x16x32_bf16 v[78:81], v[158:161], v[232:235], v[78:81]
	v_mfma_f32_16x16x32_bf16 v[74:77], v[170:173], v[232:235], v[74:77]
	s_setprio 0
	s_setprio 1
	v_mfma_f32_16x16x32_bf16 v[118:121], v[174:177], v[190:193], v[118:121]
	v_mfma_f32_16x16x32_bf16 v[114:117], v[182:185], v[190:193], v[114:117]
	v_mfma_f32_16x16x32_bf16 v[102:105], v[174:177], v[198:201], v[102:105]
	v_mfma_f32_16x16x32_bf16 v[98:101], v[182:185], v[198:201], v[98:101]
	v_mfma_f32_16x16x32_bf16 v[86:89], v[174:177], v[220:223], v[86:89]
	v_mfma_f32_16x16x32_bf16 v[82:85], v[182:185], v[220:223], v[82:85]
	v_mfma_f32_16x16x32_bf16 v[70:73], v[174:177], v[228:231], v[70:73]
	v_mfma_f32_16x16x32_bf16 v[66:69], v[182:185], v[228:231], v[66:69]
	v_mfma_f32_16x16x32_bf16 v[118:121], v[178:181], v[194:197], v[118:121]
	v_mfma_f32_16x16x32_bf16 v[114:117], v[186:189], v[194:197], v[114:117]
	v_mfma_f32_16x16x32_bf16 v[102:105], v[178:181], v[216:219], v[102:105]
	v_mfma_f32_16x16x32_bf16 v[98:101], v[186:189], v[216:219], v[98:101]
	v_mfma_f32_16x16x32_bf16 v[86:89], v[178:181], v[224:227], v[86:89]
	v_mfma_f32_16x16x32_bf16 v[82:85], v[186:189], v[224:227], v[82:85]
	v_mfma_f32_16x16x32_bf16 v[70:73], v[178:181], v[232:235], v[70:73]
	v_mfma_f32_16x16x32_bf16 v[66:69], v[186:189], v[232:235], v[66:69]
	s_setprio 0
	s_barrier
	s_add_i32 s14, s60, s29
	s_mov_b32 m0, s14
	ds_read_b128 v[190:193], v169 offset:49152
	ds_read_b128 v[194:197], v169 offset:50176
	ds_read_b128 v[198:201], v169 offset:51200
	ds_read_b128 v[216:219], v169 offset:52224
	ds_read_b128 v[220:223], v169 offset:53248
	ds_read_b128 v[224:227], v169 offset:54272
	ds_read_b128 v[228:231], v169 offset:55296
	ds_read_b128 v[232:235], v169 offset:56320
	global_load_lds_dwordx4 v138, s[72:73]
	s_add_i32 m0, s14, 0x2000
	s_add_u32 s10, s10, 0x80080
	s_addc_u32 s11, s11, 0
	s_add_i32 s14, s61, s29
	global_load_lds_dwordx4 v134, s[72:73]
	s_mov_b32 m0, s14
	s_nop 0
	global_load_lds_dwordx4 v138, s[10:11]
	s_add_i32 m0, s14, 0x2000
	s_nop 0
	global_load_lds_dwordx4 v134, s[10:11]
	s_mov_b32 m0, s52
	s_nop 0
	global_load_lds_dwordx4 v140, s[74:75]
	s_mov_b32 m0, s53
	s_nop 0
	global_load_lds_dwordx4 v136, s[74:75]
	s_waitcnt vmcnt(8)
	s_waitcnt lgkmcnt(0)
	s_barrier
	s_setprio 1
	s_waitcnt lgkmcnt(0)
	v_mfma_f32_16x16x32_bf16 v[62:65], v[130:133], v[190:193], v[62:65]
	v_mfma_f32_16x16x32_bf16 v[58:61], v[162:165], v[190:193], v[58:61]
	v_mfma_f32_16x16x32_bf16 v[46:49], v[130:133], v[198:201], v[46:49]
	v_mfma_f32_16x16x32_bf16 v[42:45], v[162:165], v[198:201], v[42:45]
	v_mfma_f32_16x16x32_bf16 v[30:33], v[130:133], v[220:223], v[30:33]
	v_mfma_f32_16x16x32_bf16 v[26:29], v[162:165], v[220:223], v[26:29]
	v_mfma_f32_16x16x32_bf16 v[14:17], v[130:133], v[228:231], v[14:17]
	v_mfma_f32_16x16x32_bf16 v[10:13], v[162:165], v[228:231], v[10:13]
	v_mfma_f32_16x16x32_bf16 v[62:65], v[158:161], v[194:197], v[62:65]
	v_mfma_f32_16x16x32_bf16 v[58:61], v[170:173], v[194:197], v[58:61]
	v_mfma_f32_16x16x32_bf16 v[46:49], v[158:161], v[216:219], v[46:49]
	v_mfma_f32_16x16x32_bf16 v[42:45], v[170:173], v[216:219], v[42:45]
	v_mfma_f32_16x16x32_bf16 v[30:33], v[158:161], v[224:227], v[30:33]
	v_mfma_f32_16x16x32_bf16 v[26:29], v[170:173], v[224:227], v[26:29]
	v_mfma_f32_16x16x32_bf16 v[14:17], v[158:161], v[232:235], v[14:17]
	v_mfma_f32_16x16x32_bf16 v[10:13], v[170:173], v[232:235], v[10:13]
	s_setprio 0
	s_setprio 1
	v_mfma_f32_16x16x32_bf16 v[54:57], v[174:177], v[190:193], v[54:57]
	v_mfma_f32_16x16x32_bf16 v[50:53], v[182:185], v[190:193], v[50:53]
	v_mfma_f32_16x16x32_bf16 v[38:41], v[174:177], v[198:201], v[38:41]
	v_mfma_f32_16x16x32_bf16 v[34:37], v[182:185], v[198:201], v[34:37]
	v_mfma_f32_16x16x32_bf16 v[22:25], v[174:177], v[220:223], v[22:25]
	v_mfma_f32_16x16x32_bf16 v[18:21], v[182:185], v[220:223], v[18:21]
	v_mfma_f32_16x16x32_bf16 v[6:9], v[174:177], v[228:231], v[6:9]
	v_mfma_f32_16x16x32_bf16 v[2:5], v[182:185], v[228:231], v[2:5]
	v_mfma_f32_16x16x32_bf16 v[54:57], v[178:181], v[194:197], v[54:57]
	v_mfma_f32_16x16x32_bf16 v[50:53], v[186:189], v[194:197], v[50:53]
	v_mfma_f32_16x16x32_bf16 v[38:41], v[178:181], v[216:219], v[38:41]
	v_mfma_f32_16x16x32_bf16 v[34:37], v[186:189], v[216:219], v[34:37]
	v_mfma_f32_16x16x32_bf16 v[22:25], v[178:181], v[224:227], v[22:25]
	v_mfma_f32_16x16x32_bf16 v[18:21], v[186:189], v[224:227], v[18:21]
	v_mfma_f32_16x16x32_bf16 v[6:9], v[178:181], v[232:235], v[6:9]
	v_mfma_f32_16x16x32_bf16 v[2:5], v[186:189], v[232:235], v[2:5]
	s_setprio 0
	s_barrier
	s_add_i32 s59, s59, 2
	s_add_u32 s57, s57, 0x100
	s_addc_u32 s58, s58, 0
	s_add_u32 s8, s8, 0x100
	s_addc_u32 s9, s9, 0
	s_cmp_gt_u32 s59, 29
	s_cbranch_scc0 .LBB0_140
	s_and_b64 vcc, exec, s[20:21]
	s_cbranch_vccz .LBB0_143
	s_barrier

.LBB0_772:
	s_add_u32 s60, s26, 0xfff80080
	s_addc_u32 s61, s27, -1
	s_add_i32 s62, 0, 0x10000
	s_cmp_eq_u32 s59, 28
	s_cselect_b32 s87, s0, s61
	s_cselect_b32 s86, s1, s60
	v_add_u32_e32 v140, s62, v143
	s_cselect_b32 s81, s13, s58
	s_cselect_b32 s80, s15, s57
	s_add_i32 s63, 0, 0x14000
	ds_read_b128 v[156:159], v140
	ds_read_b128 v[160:163], v140 offset:1024
	ds_read_b128 v[164:167], v140 offset:2048
	ds_read_b128 v[168:171], v140 offset:3072
	v_add_u32_e32 v140, s63, v143
	ds_read_b128 v[172:175], v140
	ds_read_b128 v[176:179], v140 offset:1024
	ds_read_b128 v[180:183], v140 offset:2048
	ds_read_b128 v[184:187], v140 offset:3072
	s_add_i32 m0, s48, 0xc000
	ds_read_b128 v[188:191], v145
	ds_read_b128 v[192:195], v145 offset:1024
	ds_read_b128 v[196:199], v145 offset:2048
	ds_read_b128 v[200:203], v145 offset:3072
	ds_read_b128 v[218:221], v145 offset:4096
	ds_read_b128 v[222:225], v145 offset:5120
	ds_read_b128 v[226:229], v145 offset:6144
	ds_read_b128 v[230:233], v145 offset:7168
	global_load_lds_dwordx4 v138, s[26:27]
	s_add_i32 m0, s48, 0xe000
	s_nop 0
	global_load_lds_dwordx4 v136, s[26:27]
	s_waitcnt vmcnt(8)
	s_waitcnt lgkmcnt(0)
	s_barrier
	s_setprio 1
	s_waitcnt lgkmcnt(0)
	v_mfma_f32_16x16x32_bf16 v[126:129], v[156:159], v[188:191], v[126:129]
	v_mfma_f32_16x16x32_bf16 v[122:125], v[164:167], v[188:191], v[122:125]
	v_mfma_f32_16x16x32_bf16 v[118:121], v[156:159], v[196:199], v[118:121]
	v_mfma_f32_16x16x32_bf16 v[110:113], v[164:167], v[196:199], v[110:113]
	v_mfma_f32_16x16x32_bf16 v[102:105], v[156:159], v[218:221], v[102:105]
	v_mfma_f32_16x16x32_bf16 v[94:97], v[164:167], v[218:221], v[94:97]
	v_mfma_f32_16x16x32_bf16 v[86:89], v[156:159], v[226:229], v[86:89]
	v_mfma_f32_16x16x32_bf16 v[78:81], v[164:167], v[226:229], v[78:81]
	v_mfma_f32_16x16x32_bf16 v[126:129], v[160:163], v[192:195], v[126:129]
	v_mfma_f32_16x16x32_bf16 v[122:125], v[168:171], v[192:195], v[122:125]
	v_mfma_f32_16x16x32_bf16 v[118:121], v[160:163], v[200:203], v[118:121]
	v_mfma_f32_16x16x32_bf16 v[110:113], v[168:171], v[200:203], v[110:113]
	v_mfma_f32_16x16x32_bf16 v[102:105], v[160:163], v[222:225], v[102:105]
	v_mfma_f32_16x16x32_bf16 v[94:97], v[168:171], v[222:225], v[94:97]
	v_mfma_f32_16x16x32_bf16 v[86:89], v[160:163], v[230:233], v[86:89]
	v_mfma_f32_16x16x32_bf16 v[78:81], v[168:171], v[230:233], v[78:81]
	s_setprio 0
	s_setprio 1
	v_mfma_f32_16x16x32_bf16 v[114:117], v[172:175], v[188:191], v[114:117]
	v_mfma_f32_16x16x32_bf16 v[106:109], v[180:183], v[188:191], v[106:109]
	v_mfma_f32_16x16x32_bf16 v[98:101], v[172:175], v[196:199], v[98:101]
	v_mfma_f32_16x16x32_bf16 v[90:93], v[180:183], v[196:199], v[90:93]
	v_mfma_f32_16x16x32_bf16 v[82:85], v[172:175], v[218:221], v[82:85]
	v_mfma_f32_16x16x32_bf16 v[74:77], v[180:183], v[218:221], v[74:77]
	v_mfma_f32_16x16x32_bf16 v[70:73], v[172:175], v[226:229], v[70:73]
	v_mfma_f32_16x16x32_bf16 v[66:69], v[180:183], v[226:229], v[66:69]
	v_mfma_f32_16x16x32_bf16 v[114:117], v[176:179], v[192:195], v[114:117]
	v_mfma_f32_16x16x32_bf16 v[106:109], v[184:187], v[192:195], v[106:109]
	v_mfma_f32_16x16x32_bf16 v[98:101], v[176:179], v[200:203], v[98:101]
	v_mfma_f32_16x16x32_bf16 v[90:93], v[184:187], v[200:203], v[90:93]
	v_mfma_f32_16x16x32_bf16 v[82:85], v[176:179], v[222:225], v[82:85]
	v_mfma_f32_16x16x32_bf16 v[74:77], v[184:187], v[222:225], v[74:77]
	v_mfma_f32_16x16x32_bf16 v[70:73], v[176:179], v[230:233], v[70:73]
	v_mfma_f32_16x16x32_bf16 v[66:69], v[184:187], v[230:233], v[66:69]
	s_setprio 0
	s_barrier
	s_add_i32 s60, s62, s29
	s_add_u32 s88, s80, s44
	s_addc_u32 s89, s81, s45
	s_mov_b32 m0, s60
	ds_read_b128 v[188:191], v145 offset:16384
	ds_read_b128 v[192:195], v145 offset:17408
	ds_read_b128 v[196:199], v145 offset:18432
	ds_read_b128 v[200:203], v145 offset:19456
	ds_read_b128 v[218:221], v145 offset:20480
	ds_read_b128 v[222:225], v145 offset:21504
	ds_read_b128 v[226:229], v145 offset:22528
	ds_read_b128 v[230:233], v145 offset:23552
	global_load_lds_dwordx4 v0, s[80:81]
	s_add_i32 m0, s60, 0x2000
	s_add_u32 s60, s80, 0x80000
	s_addc_u32 s61, s81, 0
	s_add_i32 s62, s63, s29
	global_load_lds_dwordx4 v130, s[80:81]
	s_mov_b32 m0, s62
	s_add_u32 s100, s86, s44
	s_addc_u32 s101, s87, s45
	global_load_lds_dwordx4 v0, s[60:61]
	s_add_i32 m0, s62, 0x2000
	s_nop 0
	global_load_lds_dwordx4 v130, s[60:61]
	s_mov_b32 m0, s48
	s_nop 0
	global_load_lds_dwordx4 v134, s[86:87]
	s_mov_b32 m0, s49
	s_nop 0
	global_load_lds_dwordx4 v132, s[86:87]
	s_waitcnt vmcnt(8)
	s_waitcnt lgkmcnt(0)
	s_barrier
	s_setprio 1
	s_waitcnt lgkmcnt(0)
	v_mfma_f32_16x16x32_bf16 v[62:65], v[156:159], v[188:191], v[62:65]
	v_mfma_f32_16x16x32_bf16 v[58:61], v[164:167], v[188:191], v[58:61]
	v_mfma_f32_16x16x32_bf16 v[54:57], v[156:159], v[196:199], v[54:57]
	v_mfma_f32_16x16x32_bf16 v[46:49], v[164:167], v[196:199], v[46:49]
	v_mfma_f32_16x16x32_bf16 v[38:41], v[156:159], v[218:221], v[38:41]
	v_mfma_f32_16x16x32_bf16 v[30:33], v[164:167], v[218:221], v[30:33]
	v_mfma_f32_16x16x32_bf16 v[22:25], v[156:159], v[226:229], v[22:25]
	v_mfma_f32_16x16x32_bf16 v[14:17], v[164:167], v[226:229], v[14:17]
	v_mfma_f32_16x16x32_bf16 v[62:65], v[160:163], v[192:195], v[62:65]
	v_mfma_f32_16x16x32_bf16 v[58:61], v[168:171], v[192:195], v[58:61]
	v_mfma_f32_16x16x32_bf16 v[54:57], v[160:163], v[200:203], v[54:57]
	v_mfma_f32_16x16x32_bf16 v[46:49], v[168:171], v[200:203], v[46:49]
	v_mfma_f32_16x16x32_bf16 v[38:41], v[160:163], v[222:225], v[38:41]
	v_mfma_f32_16x16x32_bf16 v[30:33], v[168:171], v[222:225], v[30:33]
	v_mfma_f32_16x16x32_bf16 v[22:25], v[160:163], v[230:233], v[22:25]
	v_mfma_f32_16x16x32_bf16 v[14:17], v[168:171], v[230:233], v[14:17]
	s_setprio 0
	s_setprio 1
	v_mfma_f32_16x16x32_bf16 v[50:53], v[172:175], v[188:191], v[50:53]
	v_mfma_f32_16x16x32_bf16 v[42:45], v[180:183], v[188:191], v[42:45]
	v_mfma_f32_16x16x32_bf16 v[34:37], v[172:175], v[196:199], v[34:37]
	v_mfma_f32_16x16x32_bf16 v[26:29], v[180:183], v[196:199], v[26:29]
	v_mfma_f32_16x16x32_bf16 v[18:21], v[172:175], v[218:221], v[18:21]
	v_mfma_f32_16x16x32_bf16 v[10:13], v[180:183], v[218:221], v[10:13]
	v_mfma_f32_16x16x32_bf16 v[6:9], v[172:175], v[226:229], v[6:9]
	v_mfma_f32_16x16x32_bf16 v[2:5], v[180:183], v[226:229], v[2:5]
	v_mfma_f32_16x16x32_bf16 v[50:53], v[176:179], v[192:195], v[50:53]
	v_mfma_f32_16x16x32_bf16 v[42:45], v[184:187], v[192:195], v[42:45]
	v_mfma_f32_16x16x32_bf16 v[34:37], v[176:179], v[200:203], v[34:37]
	v_mfma_f32_16x16x32_bf16 v[26:29], v[184:187], v[200:203], v[26:29]
	v_mfma_f32_16x16x32_bf16 v[18:21], v[176:179], v[222:225], v[18:21]
	v_mfma_f32_16x16x32_bf16 v[10:13], v[184:187], v[222:225], v[10:13]
	v_mfma_f32_16x16x32_bf16 v[6:9], v[176:179], v[230:233], v[6:9]
	v_mfma_f32_16x16x32_bf16 v[2:5], v[184:187], v[230:233], v[2:5]
	s_setprio 0
	s_barrier
	s_add_i32 s62, 0, 0x18000
	s_add_i32 s63, 0, 0x1c000
	v_add_u32_e32 v168, s62, v143
	v_add_u32_e32 v184, s63, v143
	ds_read_b128 v[156:159], v168
	ds_read_b128 v[160:163], v168 offset:1024
	ds_read_b128 v[164:167], v168 offset:2048
	ds_read_b128 v[168:171], v168 offset:3072
	ds_read_b128 v[172:175], v184
	ds_read_b128 v[176:179], v184 offset:1024
	ds_read_b128 v[180:183], v184 offset:2048
	ds_read_b128 v[184:187], v184 offset:3072
	s_add_u32 s60, s86, 0x80000
	s_addc_u32 s61, s87, 0
	s_mov_b32 m0, s50
	ds_read_b128 v[188:191], v145 offset:32768
	ds_read_b128 v[192:195], v145 offset:33792
	ds_read_b128 v[196:199], v145 offset:34816
	ds_read_b128 v[200:203], v145 offset:35840
	ds_read_b128 v[218:221], v145 offset:36864
	ds_read_b128 v[222:225], v145 offset:37888
	ds_read_b128 v[226:229], v145 offset:38912
	ds_read_b128 v[230:233], v145 offset:39936
	global_load_lds_dwordx4 v134, s[60:61]
	s_mov_b32 m0, s51
	s_nop 0
	global_load_lds_dwordx4 v132, s[60:61]
	s_waitcnt vmcnt(8)
	s_waitcnt lgkmcnt(0)
	s_barrier
	s_setprio 1
	s_waitcnt lgkmcnt(0)
	v_mfma_f32_16x16x32_bf16 v[126:129], v[156:159], v[188:191], v[126:129]
	v_mfma_f32_16x16x32_bf16 v[122:125], v[164:167], v[188:191], v[122:125]
	v_mfma_f32_16x16x32_bf16 v[118:121], v[156:159], v[196:199], v[118:121]
	v_mfma_f32_16x16x32_bf16 v[110:113], v[164:167], v[196:199], v[110:113]
	v_mfma_f32_16x16x32_bf16 v[102:105], v[156:159], v[218:221], v[102:105]
	v_mfma_f32_16x16x32_bf16 v[94:97], v[164:167], v[218:221], v[94:97]
	v_mfma_f32_16x16x32_bf16 v[86:89], v[156:159], v[226:229], v[86:89]
	v_mfma_f32_16x16x32_bf16 v[78:81], v[164:167], v[226:229], v[78:81]
	v_mfma_f32_16x16x32_bf16 v[126:129], v[160:163], v[192:195], v[126:129]
	v_mfma_f32_16x16x32_bf16 v[122:125], v[168:171], v[192:195], v[122:125]
	v_mfma_f32_16x16x32_bf16 v[118:121], v[160:163], v[200:203], v[118:121]
	v_mfma_f32_16x16x32_bf16 v[110:113], v[168:171], v[200:203], v[110:113]
	v_mfma_f32_16x16x32_bf16 v[102:105], v[160:163], v[222:225], v[102:105]
	v_mfma_f32_16x16x32_bf16 v[94:97], v[168:171], v[222:225], v[94:97]
	v_mfma_f32_16x16x32_bf16 v[86:89], v[160:163], v[230:233], v[86:89]
	v_mfma_f32_16x16x32_bf16 v[78:81], v[168:171], v[230:233], v[78:81]
	s_setprio 0
	s_setprio 1
	v_mfma_f32_16x16x32_bf16 v[114:117], v[172:175], v[188:191], v[114:117]
	v_mfma_f32_16x16x32_bf16 v[106:109], v[180:183], v[188:191], v[106:109]
	v_mfma_f32_16x16x32_bf16 v[98:101], v[172:175], v[196:199], v[98:101]
	v_mfma_f32_16x16x32_bf16 v[90:93], v[180:183], v[196:199], v[90:93]
	v_mfma_f32_16x16x32_bf16 v[82:85], v[172:175], v[218:221], v[82:85]
	v_mfma_f32_16x16x32_bf16 v[74:77], v[180:183], v[218:221], v[74:77]
	v_mfma_f32_16x16x32_bf16 v[70:73], v[172:175], v[226:229], v[70:73]
	v_mfma_f32_16x16x32_bf16 v[66:69], v[180:183], v[226:229], v[66:69]
	v_mfma_f32_16x16x32_bf16 v[114:117], v[176:179], v[192:195], v[114:117]
	v_mfma_f32_16x16x32_bf16 v[106:109], v[184:187], v[192:195], v[106:109]
	v_mfma_f32_16x16x32_bf16 v[98:101], v[176:179], v[200:203], v[98:101]
	v_mfma_f32_16x16x32_bf16 v[90:93], v[184:187], v[200:203], v[90:93]
	v_mfma_f32_16x16x32_bf16 v[82:85], v[176:179], v[222:225], v[82:85]
	v_mfma_f32_16x16x32_bf16 v[74:77], v[184:187], v[222:225], v[74:77]
	v_mfma_f32_16x16x32_bf16 v[70:73], v[176:179], v[230:233], v[70:73]
	v_mfma_f32_16x16x32_bf16 v[66:69], v[184:187], v[230:233], v[66:69]
	s_setprio 0
	s_barrier
	s_add_i32 s60, s62, s29
	s_mov_b32 m0, s60
	ds_read_b128 v[188:191], v145 offset:49152
	ds_read_b128 v[192:195], v145 offset:50176
	ds_read_b128 v[196:199], v145 offset:51200
	ds_read_b128 v[200:203], v145 offset:52224
	ds_read_b128 v[218:221], v145 offset:53248
	ds_read_b128 v[222:225], v145 offset:54272
	ds_read_b128 v[226:229], v145 offset:55296
	ds_read_b128 v[230:233], v145 offset:56320
	global_load_lds_dwordx4 v0, s[88:89]
	s_add_i32 m0, s60, 0x2000
	s_add_u32 s60, s80, 0x80080
	s_addc_u32 s61, s81, 0
	s_add_i32 s62, s63, s29
	global_load_lds_dwordx4 v130, s[88:89]
	s_mov_b32 m0, s62
	s_nop 0
	global_load_lds_dwordx4 v0, s[60:61]
	s_add_i32 m0, s62, 0x2000
	s_nop 0
	global_load_lds_dwordx4 v130, s[60:61]
	s_mov_b32 m0, s52
	s_nop 0
	global_load_lds_dwordx4 v134, s[100:101]
	s_mov_b32 m0, s53
	s_nop 0
	global_load_lds_dwordx4 v132, s[100:101]
	s_waitcnt vmcnt(8)
	s_waitcnt lgkmcnt(0)
	s_barrier
	s_setprio 1
	s_waitcnt lgkmcnt(0)
	v_mfma_f32_16x16x32_bf16 v[62:65], v[156:159], v[188:191], v[62:65]
	v_mfma_f32_16x16x32_bf16 v[58:61], v[164:167], v[188:191], v[58:61]
	v_mfma_f32_16x16x32_bf16 v[54:57], v[156:159], v[196:199], v[54:57]
	v_mfma_f32_16x16x32_bf16 v[46:49], v[164:167], v[196:199], v[46:49]
	v_mfma_f32_16x16x32_bf16 v[38:41], v[156:159], v[218:221], v[38:41]
	v_mfma_f32_16x16x32_bf16 v[30:33], v[164:167], v[218:221], v[30:33]
	v_mfma_f32_16x16x32_bf16 v[22:25], v[156:159], v[226:229], v[22:25]
	v_mfma_f32_16x16x32_bf16 v[14:17], v[164:167], v[226:229], v[14:17]
	v_mfma_f32_16x16x32_bf16 v[62:65], v[160:163], v[192:195], v[62:65]
	v_mfma_f32_16x16x32_bf16 v[58:61], v[168:171], v[192:195], v[58:61]
	v_mfma_f32_16x16x32_bf16 v[54:57], v[160:163], v[200:203], v[54:57]
	v_mfma_f32_16x16x32_bf16 v[46:49], v[168:171], v[200:203], v[46:49]
	v_mfma_f32_16x16x32_bf16 v[38:41], v[160:163], v[222:225], v[38:41]
	v_mfma_f32_16x16x32_bf16 v[30:33], v[168:171], v[222:225], v[30:33]
	v_mfma_f32_16x16x32_bf16 v[22:25], v[160:163], v[230:233], v[22:25]
	v_mfma_f32_16x16x32_bf16 v[14:17], v[168:171], v[230:233], v[14:17]
	s_setprio 0
	s_setprio 1
	v_mfma_f32_16x16x32_bf16 v[50:53], v[172:175], v[188:191], v[50:53]
	v_mfma_f32_16x16x32_bf16 v[42:45], v[180:183], v[188:191], v[42:45]
	v_mfma_f32_16x16x32_bf16 v[34:37], v[172:175], v[196:199], v[34:37]
	v_mfma_f32_16x16x32_bf16 v[26:29], v[180:183], v[196:199], v[26:29]
	v_mfma_f32_16x16x32_bf16 v[18:21], v[172:175], v[218:221], v[18:21]
	v_mfma_f32_16x16x32_bf16 v[10:13], v[180:183], v[218:221], v[10:13]
	v_mfma_f32_16x16x32_bf16 v[6:9], v[172:175], v[226:229], v[6:9]
	v_mfma_f32_16x16x32_bf16 v[2:5], v[180:183], v[226:229], v[2:5]
	v_mfma_f32_16x16x32_bf16 v[50:53], v[176:179], v[192:195], v[50:53]
	v_mfma_f32_16x16x32_bf16 v[42:45], v[184:187], v[192:195], v[42:45]
	v_mfma_f32_16x16x32_bf16 v[34:37], v[176:179], v[200:203], v[34:37]
	v_mfma_f32_16x16x32_bf16 v[26:29], v[184:187], v[200:203], v[26:29]
	v_mfma_f32_16x16x32_bf16 v[18:21], v[176:179], v[222:225], v[18:21]
	v_mfma_f32_16x16x32_bf16 v[10:13], v[184:187], v[222:225], v[10:13]
	v_mfma_f32_16x16x32_bf16 v[6:9], v[176:179], v[230:233], v[6:9]
	v_mfma_f32_16x16x32_bf16 v[2:5], v[184:187], v[230:233], v[2:5]
	s_setprio 0
	s_barrier
	s_add_i32 s59, s59, 2
	s_add_u32 s57, s57, 0x100
	s_addc_u32 s58, s58, 0
	s_add_u32 s26, s26, 0x100
	s_addc_u32 s27, s27, 0
	s_cmp_gt_u32 s59, 29
	s_cbranch_scc0 .LBB0_772
	s_and_b64 vcc, exec, s[10:11]
	v_readlane_b32 s58, v254, 35
	v_readlane_b32 s59, v254, 36
	s_cbranch_vccz .LBB0_775
	s_barrier
